# v11 + in-projection epilogue: row group 7 rotary-table loads issued one group early
# speedup vs baseline: 1.0049x; 1.0049x over previous
; DI unsigned pk2(float lo, float hi) { f32x2 v = {lo, hi}; bf16x2_t b = __builtin_convertvector(v, bf16x2_t); return __builtin_bit_cast(unsigned, b); }
;     DI void operator()(const pg8::f32x4 (&acc)[2][2][4][2], const pg8::Unit& u, int wr, int wc, int fr, int fq) const {
;     ...
;                 if ((att || ret) && row < M_LAT) {
;                     rot = true;
;                     const int s = row & 4095;
;                     const f32x2* tp;
;                     if (att) { const int pos = (wc & 1) ? (s & 63) : (s >> 6); tp = tatt + pos * 16 + 4 * fq; }
;                     else { tp = tret + (size_t)s * 32 + 16 * (wc & 1) + 4 * fq; }
;                     const f32x4 t0 = *(const f32x4*)tp, t1 = *(const f32x4*)(tp + 2);
;                     cs[0] = (f32x2){t0.x, t0.y}; cs[1] = (f32x2){t0.z, t0.w}; cs[2] = (f32x2){t1.x, t1.y}; cs[3] = (f32x2){t1.z, t1.w};
;                 }
; #pragma unroll
;                 for (int bj = 0; bj < 2; ++bj) {
;                     float v[8];
; #pragma unroll
;                     for (int n = 0; n < 2; ++n)
; #pragma unroll
;                         for (int j = 0; j < 4; ++j) v[n * 4 + j] = acc[ai][bj][m][n][j];
;                     if (rot) {
; #pragma unroll
;                         for (int q = 0; q < 4; ++q) { const float h1 = v[2 * q], h2 = v[2 * q + 1]; v[2 * q] = h1 * cs[q].x - h2 * cs[q].y; v[2 * q + 1] = h2 * cs[q].x + h1 * cs[q].y; }
;                     }
;                     u32x4 w; w.x = pk2(v[0] * sc, v[1] * sc); w.y = pk2(v[2] * sc, v[3] * sc); w.z = pk2(v[4] * sc, v[5] * sc); w.w = pk2(v[6] * sc, v[7] * sc);
.LBB0_154:
	s_or_b64 exec, exec, s[28:29]
	v_pk_mul_f32 v[150:151], v[164:165], v[170:171]
	s_nop 0
	v_cvt_pk_bf16_f32 v170, v150, v151
	v_pk_mul_f32 v[150:151], v[164:165], v[172:173]
	s_nop 0
	v_cvt_pk_bf16_f32 v171, v150, v151
	v_pk_mul_f32 v[150:151], v[164:165], v[174:175]
	s_nop 0
	v_cvt_pk_bf16_f32 v172, v150, v151
	v_pk_mul_f32 v[150:151], v[164:165], v[176:177]
	s_nop 0
	v_cvt_pk_bf16_f32 v173, v150, v151
	global_store_dwordx4 v[168:169], v[170:173], off offset:256
	s_movk_i32 s0, 0x7f80
	v_cmp_gt_i32_e64 s[0:1], s0, v180
	v_add_u32_e32 v176, 0x80, v180
	s_and_b64 s[0:1], s[2:3], s[0:1]
	s_and_saveexec_b64 s[28:29], s[0:1]
	s_cbranch_execz .LBB0_156
	s_waitcnt vmcnt(2)
	v_bfe_u32 v129, v176, 6, 6
	v_and_b32_e32 v128, 0xfcf, v176
	v_cndmask_b32_e64 v129, v153, v129, s[6:7]
	v_lshlrev_b32_e32 v129, 4, v129
	v_lshlrev_b32_e32 v128, 5, v128
	v_cndmask_b32_e32 v128, v128, v129, vcc
	s_and_b64 s[52:53], vcc, exec
	s_cselect_b32 s53, s41, s49
	s_cselect_b32 s52, s40, s48
	v_lshlrev_b32_e32 v128, 3, v128
	v_mov_b32_e32 v129, v147
	v_lshl_add_u64 v[128:129], s[52:53], 0, v[128:129]
	v_mov_b32_e32 v167, v147
	v_lshl_add_u64 v[132:133], v[128:129], 0, v[166:167]
	v_mov_b32_e32 v128, v230
	v_mov_b32_e32 v129, v231
	v_mov_b32_e32 v130, v232
	v_mov_b32_e32 v131, v233
	s_nop 0
	v_mov_b32_e32 v132, v226
	v_mov_b32_e32 v133, v227
	v_mov_b32_e32 v134, v228
	v_mov_b32_e32 v135, v229
	v_add_u32_e32 v206, 0xb0, v180
	v_bfe_u32 v207, v206, 6, 6
	v_and_b32_e32 v206, 0xfff, v206
	v_cndmask_b32_e64 v207, v159, v207, s[6:7]
	v_lshlrev_b32_e32 v207, 4, v207
	v_lshlrev_b32_e32 v206, 5, v206
	v_cndmask_b32_e32 v206, v206, v207, vcc
	v_lshlrev_b32_e32 v206, 3, v206
	v_mov_b32_e32 v207, v147
	v_lshl_add_u64 v[206:207], s[52:53], 0, v[206:207]
	v_lshl_add_u64 v[206:207], v[206:207], 0, v[166:167]
	global_load_dwordx4 v[190:193], v[206:207], off
	global_load_dwordx4 v[194:197], v[206:207], off offset:16

;     DI void operator()(const pg8::f32x4 (&acc)[2][2][4][2], const pg8::Unit& u, int wr, int wc, int fr, int fq) const {
;     ...
;                 if ((att || ret) && row < M_LAT) {
;                     rot = true;
;                     const int s = row & 4095;
;                     const f32x2* tp;
;                     if (att) { const int pos = (wc & 1) ? (s & 63) : (s >> 6); tp = tatt + pos * 16 + 4 * fq; }
;                     else { tp = tret + (size_t)s * 32 + 16 * (wc & 1) + 4 * fq; }
;                     const f32x4 t0 = *(const f32x4*)tp, t1 = *(const f32x4*)(tp + 2);
;                     cs[0] = (f32x2){t0.x, t0.y}; cs[1] = (f32x2){t0.z, t0.w}; cs[2] = (f32x2){t1.x, t1.y}; cs[3] = (f32x2){t1.z, t1.w};
.LBB0_172:
	s_or_b64 exec, exec, s[28:29]
	v_pk_mul_f32 v[150:151], v[164:165], v[170:171]
	s_nop 0
	v_cvt_pk_bf16_f32 v170, v150, v151
	v_pk_mul_f32 v[150:151], v[164:165], v[172:173]
	s_nop 0
	v_cvt_pk_bf16_f32 v171, v150, v151
	v_pk_mul_f32 v[150:151], v[164:165], v[174:175]
	s_nop 0
	v_cvt_pk_bf16_f32 v172, v150, v151
	v_pk_mul_f32 v[150:151], v[164:165], v[176:177]
	s_nop 0
	v_cvt_pk_bf16_f32 v173, v150, v151
	global_store_dwordx4 v[168:169], v[170:173], off offset:256
	s_movk_i32 s0, 0x7f50
	v_cmp_gt_i32_e64 s[0:1], s0, v180
	v_add_u32_e32 v174, 0xb0, v180
	s_and_b64 s[0:1], s[2:3], s[0:1]
	s_and_saveexec_b64 s[2:3], s[0:1]
	s_cbranch_execz .LBB0_174
	s_waitcnt vmcnt(2)
	v_bfe_u32 v129, v174, 6, 6
	v_and_b32_e32 v128, 0xfff, v174
	v_cndmask_b32_e64 v129, v159, v129, s[6:7]
	v_lshlrev_b32_e32 v129, 4, v129
	v_lshlrev_b32_e32 v128, 5, v128
	v_cndmask_b32_e32 v128, v128, v129, vcc
	s_and_b64 s[28:29], vcc, exec
	s_cselect_b32 s29, s41, s49
	s_cselect_b32 s28, s40, s48
	v_lshlrev_b32_e32 v128, 3, v128
	v_mov_b32_e32 v129, v147
	v_lshl_add_u64 v[128:129], s[28:29], 0, v[128:129]
	v_mov_b32_e32 v167, v147
	v_lshl_add_u64 v[132:133], v[128:129], 0, v[166:167]
	v_mov_b32_e32 v128, v194
	v_mov_b32_e32 v129, v195
	v_mov_b32_e32 v130, v196
	v_mov_b32_e32 v131, v197
	s_nop 0
	v_mov_b32_e32 v132, v190
	v_mov_b32_e32 v133, v191
	v_mov_b32_e32 v134, v192
	v_mov_b32_e32 v135, v193
